# as previous but all waves use the immediate-PV fast body (no wave-half stagger): simpler DA loop
# baseline (speedup 1.0000x reference)
; #define FA_PREFETCH(kt_) do { int k0_ = (kt_) * 64; \
;     _Pragma("unroll") for (int i = 0; i < KPT; ++i) kreg[i] = __builtin_amdgcn_raw_buffer_load_b128(rsK, kvo[i], k0_ * k_stride * 2, 0); \
;     _Pragma("unroll") for (int i = 0; i < VPT; ++i) vreg[i] = __builtin_amdgcn_raw_buffer_load_b128(rsV, vvo[i], k0_ * 2, 0); } while (0)
; #define FA_PREFETCH_NEXT() do { \
;     _Pragma("unroll") for (int i = 0; i < KPT; ++i) kreg[i] = __builtin_amdgcn_raw_buffer_load_b128(rsNK, kvo[i], 0, 0); \
;     _Pragma("unroll") for (int i = 0; i < VPT; ++i) vreg[i] = __builtin_amdgcn_raw_buffer_load_b128(rsNV, vvo[i], 0, 0); } while (0)
; template <int NC, int DQK, int DV, bool CAUSAL, bool PF> ...
;     ...
;     u16* Kb = Ks + (kt & 1) * KBUF; u16* Vb = Vs + (kt & 1) * VBUF;
;     _Pragma("unroll") for (int i = 0; i < KPT; ++i) { int id = tid + i * 512, row = id / KCH, cc = id % KCH; *(u32x4*)&Kb[row * KLD + cc * 8] = kreg[i]; }
;     _Pragma("unroll") for (int i = 0; i < VPT; ++i) {
;       int id = tid + i * 512, row = id >> 3, cc = id & 7;
;       int pos = 32 * (cc >> 2) + 16 * (cc & 1) + 4 * ((cc >> 1) & 1);
;       uint2 lo2, hi2; lo2.x = vreg[i][0]; lo2.y = vreg[i][1]; hi2.x = vreg[i][2]; hi2.y = vreg[i][3];
;       *(uint2*)&Vb[row * VLD + pos] = lo2; *(uint2*)&Vb[row * VLD + pos + 8] = hi2;
;     }
;     __syncthreads();
;     if (PF && kt + 1 < nkt) FA_PREFETCH(kt + 1); else if (PF && has_next_item) FA_PREFETCH_NEXT();
;     int k0 = kt * 64;
;     if (CAUSAL && k0 > qw0 + 15) continue;
;     bf16x8 pf[NC][2];
;     bool general = false; float bb = 0.f;
;     if (CAUSAL) { general = (qw0 - (k0 + 63)) < 113; bb = btab[127]; }
;     f32x4 bv[4];
;     if (general) {
;       bool diag = (k0 + 63) > qw0;
;       _Pragma("unroll") for (int m = 0; m < 4; ++m) _Pragma("unroll") for (int j = 0; j < 4; ++j) {
;         int dist = qpos - (k0 + 16 * m + fq * 4 + j);
;         int di = dist < 0 ? 0 : (dist > 127 ? 127 : dist);
;         float b = btab[di];
;         bv[m][j] = (diag && dist < 0) ? -1e30f : b;
;       }
;     }
.LBB0_1785:
	s_and_b32 s0, s34, 1
	s_mul_i32 s1, s0, 0x4400
	s_add_i32 s38, s1, 0
	v_add3_u32 v0, s38, v210, v204
	s_mul_hi_u32 s0, s34, 0xaaaaaaab
	s_lshr_b32 s0, s0, 1
	s_mul_i32 s0, s0, 3
	s_sub_i32 s0, s34, s0
	s_mul_i32 s0, s0, 0x5000
	s_waitcnt vmcnt(3)
	ds_write_b128 v0, v[34:37]
	v_add3_u32 v0, s38, v209, v205
	s_mov_b32 s37, s0
	s_waitcnt vmcnt(2)
	ds_write_b128 v0, v[38:41]
	v_lshl_add_u32 v0, v206, 1, s37
	v_add3_u32 v0, v0, v211, v212
	v_add_u32_e32 v1, v0, v208
	v_add_u32_e32 v0, v0, v207
	v_add_u32_e32 v1, 0x8800, v1
	v_add_u32_e32 v0, 0x8800, v0
	s_mov_b32 s14, s78
	s_mov_b32 s15, s79
	s_waitcnt vmcnt(0)
	ds_write2_b64 v1, v[42:43], v[44:45] offset1:2
	s_waitcnt vmcnt(0)
	ds_write2_b64 v0, v[46:47], v[48:49] offset1:2
	s_waitcnt lgkmcnt(0)
	s_barrier
	buffer_load_dwordx4 v[34:37], v198, s[76:79], s36 offen
	buffer_load_dwordx4 v[38:41], v199, s[76:79], s36 offen
	buffer_load_dwordx4 v[46:49], v200, s[12:15], s31 offen
	buffer_load_dwordx4 v[42:45], v201, s[12:15], s31 offen
	s_sub_i32 s0, s35, 63
	v_cmp_le_i32_e32 vcc, s0, v203
	s_and_saveexec_b64 s[0:1], vcc
	s_cbranch_execz .LBB0_1784
	v_readlane_b32 s6, v254, 39
	v_cmp_gt_i32_e32 vcc, s35, v202
	s_nop 0
	v_mov_b32_e32 v0, s6
	ds_read_b32 v170, v0
	v_cmp_le_i32_e64 s[6:7], s35, v202
	s_cbranch_vccz .Lda_fast_sel
.Lda_gen_cont:
	s_and_saveexec_b64 s[14:15], vcc
	s_cbranch_execz .LBB0_1788
	v_add_u32_e32 v0, 51, v213
	v_add_u32_e32 v1, 50, v213
	v_add_u32_e32 v2, 49, v213
	v_add_u32_e32 v3, 48, v213
	v_add_u32_e32 v4, 35, v213
	v_add_u32_e32 v5, 34, v213
	v_add_u32_e32 v6, 33, v213
	v_add_u32_e32 v7, 32, v213
	v_add_u32_e32 v8, 19, v213
	v_add_u32_e32 v9, 18, v213
	v_add_u32_e32 v10, 17, v213
	v_add_u32_e32 v11, 16, v213
	v_add_u32_e32 v12, 3, v213
	v_add_u32_e32 v13, 2, v213
	v_add_u32_e32 v14, 1, v213
	v_mov_b32_e32 v15, v213
	v_med3_i32 v16, v0, 0, v184
	v_med3_i32 v17, v1, 0, v184
	v_med3_i32 v18, v2, 0, v184
	v_med3_i32 v19, v3, 0, v184
	v_med3_i32 v20, v4, 0, v184
	v_med3_i32 v21, v5, 0, v184
	v_med3_i32 v22, v6, 0, v184
	v_med3_i32 v23, v7, 0, v184
	v_med3_i32 v24, v8, 0, v184
	v_med3_i32 v25, v9, 0, v184
	v_med3_i32 v26, v10, 0, v184
	v_med3_i32 v27, v11, 0, v184
	v_med3_i32 v28, v12, 0, v184
	v_med3_i32 v29, v13, 0, v184
	v_med3_i32 v30, v14, 0, v184
	v_med3_i32 v31, v15, 0, v184
	v_lshl_add_u32 v16, v16, 2, s91
	v_lshl_add_u32 v17, v17, 2, s91
	v_lshl_add_u32 v18, v18, 2, s91
	v_lshl_add_u32 v19, v19, 2, s91
	v_lshl_add_u32 v20, v20, 2, s91
	v_lshl_add_u32 v21, v21, 2, s91
	v_lshl_add_u32 v22, v22, 2, s91
	v_lshl_add_u32 v23, v23, 2, s91
	v_lshl_add_u32 v24, v24, 2, s91
	v_lshl_add_u32 v25, v25, 2, s91
	v_lshl_add_u32 v26, v26, 2, s91
	v_lshl_add_u32 v27, v27, 2, s91
	v_lshl_add_u32 v28, v28, 2, s91
	v_lshl_add_u32 v29, v29, 2, s91
	v_lshl_add_u32 v30, v30, 2, s91
	v_lshl_add_u32 v31, v31, 2, s91
	ds_read_b32 v122, v16
	ds_read_b32 v123, v17
	ds_read_b32 v124, v18
	ds_read_b32 v125, v19
	ds_read_b32 v126, v20
	ds_read_b32 v127, v21
	ds_read_b32 v128, v22
	ds_read_b32 v129, v23
	s_waitcnt lgkmcnt(6)
	ds_read_b32 v130, v24
	ds_read_b32 v131, v25
	ds_read_b32 v132, v26
	ds_read_b32 v133, v27
	ds_read_b32 v142, v28
	ds_read_b32 v143, v29
	ds_read_b32 v144, v30
	ds_read_b32 v145, v31
	v_cmp_gt_i32_e32 vcc, s35, v197
	s_waitcnt lgkmcnt(0)
	s_cbranch_vccz .Ldg_nomask
	v_cmp_gt_i32_e32 vcc, 0, v0
	v_cmp_gt_i32_e64 s[8:9], 0, v1
	s_nop 0
	v_cndmask_b32_e32 v122, v122, v185, vcc
	v_cmp_gt_i32_e32 vcc, 0, v2
	v_cndmask_b32_e64 v123, v123, v185, s[8:9]
	v_cmp_gt_i32_e64 s[8:9], 0, v3
	v_cndmask_b32_e32 v124, v124, v185, vcc
	v_cmp_gt_i32_e32 vcc, 0, v4
	v_cndmask_b32_e64 v125, v125, v185, s[8:9]
	v_cmp_gt_i32_e64 s[8:9], 0, v5
	v_cndmask_b32_e32 v126, v126, v185, vcc
	v_cmp_gt_i32_e32 vcc, 0, v6
	v_cndmask_b32_e64 v127, v127, v185, s[8:9]
	v_cmp_gt_i32_e64 s[8:9], 0, v7
	v_cndmask_b32_e32 v128, v128, v185, vcc
	v_cmp_gt_i32_e32 vcc, 0, v8
	v_cndmask_b32_e64 v129, v129, v185, s[8:9]
	v_cmp_gt_i32_e64 s[8:9], 0, v9
	v_cndmask_b32_e32 v130, v130, v185, vcc
	v_cmp_gt_i32_e32 vcc, 0, v10
	v_cndmask_b32_e64 v131, v131, v185, s[8:9]
	v_cmp_gt_i32_e64 s[8:9], 0, v11
	v_cndmask_b32_e32 v132, v132, v185, vcc
	v_cmp_gt_i32_e32 vcc, 0, v12
	v_cndmask_b32_e64 v133, v133, v185, s[8:9]
	v_cmp_gt_i32_e64 s[8:9], 0, v13
	v_cndmask_b32_e32 v142, v142, v185, vcc
	v_cmp_gt_i32_e32 vcc, 0, v14
	v_cndmask_b32_e64 v143, v143, v185, s[8:9]
	v_cmp_gt_i32_e64 s[8:9], 0, v15
	v_cndmask_b32_e32 v144, v144, v185, vcc
	s_nop 0
	v_cndmask_b32_e64 v145, v145, v185, s[8:9]

; template <int NC, int DQK, int DV, bool CAUSAL, bool PF> ...
;     ...
;     _Pragma("unroll") for (int c = 0; c < NC; ++c) {
;       f32x4 s[4];
;       _Pragma("unroll") for (int m = 0; m < 4; ++m) s[m] = f32x4{0.f, 0.f, 0.f, 0.f};
;       _Pragma("unroll") for (int ks = 0; ks < NKS; ++ks) _Pragma("unroll") for (int m = 0; m < 4; ++m) {
;         bf16x8 a = *(const bf16x8*)&Kb[(16 * m + fr) * KLD + c * DQK + ks * 32 + fq * 8];
;         s[m] = __builtin_amdgcn_mfma_f32_16x16x32_bf16(a, qf[c][ks], s[m], 0, 0, 0);
;       }
;       constexpr float THR = 8.f;
;       float tnew, psum = 0.f;
;       if (general) {
;         float tmax = -1e30f;
;         _Pragma("unroll") for (int m = 0; m < 4; ++m) _Pragma("unroll") for (int j = 0; j < 4; ++j) {
;           float v = s[m][j] * scale_log2 + bv[m][j];
;           s[m][j] = v; tmax = fmaxf(tmax, v);
;         }
;         tnew = tmax;
;       } else {
;         float rmax = fmaxf(fmaxf(s[0][0], s[0][1]), fmaxf(s[0][2], s[0][3]));
;         _Pragma("unroll") for (int m = 1; m < 4; ++m) rmax = fmaxf(rmax, fmaxf(fmaxf(s[m][0], s[m][1]), fmaxf(s[m][2], s[m][3])));
;         tnew = rmax * scale_log2 + bb;
;       }
;       if (__builtin_amdgcn_ballot_w64(tnew - mrun[c] > THR) != 0ull) {
.Lda_fast_sel:
.Lda_fast:
	v_add3_u32 v172, s38, v32, v195
	v_add3_u32 v173, s37, v32, v193
	ds_read_b128 v[146:149], v172
	ds_read_b128 v[150:153], v172 offset:4352
	ds_read_b128 v[154:157], v172 offset:8704
	ds_read_b128 v[158:161], v172 offset:13056
	ds_read_b128 v[16:19], v172 offset:64
	ds_read_b128 v[20:23], v172 offset:4416
	ds_read_b128 v[24:27], v172 offset:8768
	ds_read_b128 v[28:31], v172 offset:13120
	ds_read_b128 v[0:3], v172 offset:128
	ds_read_b128 v[4:7], v172 offset:4480
	ds_read_b128 v[8:11], v172 offset:8832
	ds_read_b128 v[12:15], v172 offset:13184
	s_waitcnt lgkmcnt(10)
	v_mfma_f32_16x16x32_bf16 v[146:149], v[146:149], v[138:141], 0
	v_mfma_f32_16x16x32_bf16 v[150:153], v[150:153], v[138:141], 0
	s_waitcnt lgkmcnt(8)
	v_mfma_f32_16x16x32_bf16 v[154:157], v[154:157], v[138:141], 0
	v_mfma_f32_16x16x32_bf16 v[158:161], v[158:161], v[138:141], 0
	s_waitcnt lgkmcnt(4)
	v_mfma_f32_16x16x32_bf16 v[146:149], v[16:19], v[134:137], v[146:149]
	v_mfma_f32_16x16x32_bf16 v[150:153], v[20:23], v[134:137], v[150:153]
	v_mfma_f32_16x16x32_bf16 v[154:157], v[24:27], v[134:137], v[154:157]
	v_mfma_f32_16x16x32_bf16 v[158:161], v[28:31], v[134:137], v[158:161]
	ds_read_b128 v[16:19], v172 offset:192
	ds_read_b128 v[20:23], v172 offset:4544
	ds_read_b128 v[24:27], v172 offset:8896
	ds_read_b128 v[28:31], v172 offset:13248
	ds_read_b128 v[122:125], v173 offset:34816
	ds_read_b128 v[126:129], v173 offset:37376
	ds_read_b128 v[130:133], v173 offset:39936
	ds_read_b128 v[142:145], v173 offset:42496
	s_waitcnt lgkmcnt(8)
	v_mfma_f32_16x16x32_bf16 v[0:3], v[0:3], v[118:121], 0
	v_mfma_f32_16x16x32_bf16 v[4:7], v[4:7], v[118:121], 0
	v_mfma_f32_16x16x32_bf16 v[8:11], v[8:11], v[118:121], 0
	v_mfma_f32_16x16x32_bf16 v[12:15], v[12:15], v[118:121], 0
	v_max3_f32 v174, v146, v147, v148
	v_max3_f32 v175, v149, v150, v151
	v_max3_f32 v174, v174, v152, v153
	v_max3_f32 v175, v175, v154, v155
	v_max3_f32 v174, v174, v156, v157
	v_max3_f32 v175, v175, v158, v159
	v_max3_f32 v174, v174, v160, v161
	v_max_f32_e32 v174, v174, v175
	v_fmamk_f32 v174, v174, 0x3e38aa3b, v170
	v_sub_f32_e32 v175, v174, v194
	v_cmp_lt_f32_e32 vcc, s33, v175
	s_cbranch_vccnz .Lda_resc0

; #define FA_PREFETCH(kt_) do { int k0_ = (kt_) * 64; \
;     _Pragma("unroll") for (int i = 0; i < KPT; ++i) kreg[i] = __builtin_amdgcn_raw_buffer_load_b128(rsK, kvo[i], k0_ * k_stride * 2, 0); \
;     _Pragma("unroll") for (int i = 0; i < VPT; ++i) vreg[i] = __builtin_amdgcn_raw_buffer_load_b128(rsV, vvo[i], k0_ * 2, 0); } while (0)
; #define FA_PREFETCH_NEXT() do { \
;     _Pragma("unroll") for (int i = 0; i < KPT; ++i) kreg[i] = __builtin_amdgcn_raw_buffer_load_b128(rsNK, kvo[i], 0, 0); \
;     _Pragma("unroll") for (int i = 0; i < VPT; ++i) vreg[i] = __builtin_amdgcn_raw_buffer_load_b128(rsNV, vvo[i], 0, 0); } while (0)
; template <int NC, int DQK, int DV, bool CAUSAL, bool PF> ...
;     ...
;   for (int kt = 0; kt < nkt; ++kt) {
;     if (!PF) FA_PREFETCH(kt);
;     u16* Kb = Ks + (kt & 1) * KBUF; u16* Vb = Vs + (kt & 1) * VBUF;
;     _Pragma("unroll") for (int i = 0; i < KPT; ++i) { int id = tid + i * 512, row = id / KCH, cc = id % KCH; *(u32x4*)&Kb[row * KLD + cc * 8] = kreg[i]; }
;     _Pragma("unroll") for (int i = 0; i < VPT; ++i) {
;       int id = tid + i * 512, row = id >> 3, cc = id & 7;
;       int pos = 32 * (cc >> 2) + 16 * (cc & 1) + 4 * ((cc >> 1) & 1);
;       uint2 lo2, hi2; lo2.x = vreg[i][0]; lo2.y = vreg[i][1]; hi2.x = vreg[i][2]; hi2.y = vreg[i][3];
;       *(uint2*)&Vb[row * VLD + pos] = lo2; *(uint2*)&Vb[row * VLD + pos + 8] = hi2;
;     }
;     __syncthreads();
;     if (PF && kt + 1 < nkt) FA_PREFETCH(kt + 1); else if (PF && has_next_item) FA_PREFETCH_NEXT();
;     ...
;       if (__builtin_amdgcn_ballot_w64(tnew - mrun[c] > THR) != 0ull) {
;         tnew = fmaxf(tnew, sx<16>(tnew, lane)); tnew = fmaxf(tnew, sx<32>(tnew, lane));
;         float mnew = fmaxf(mrun[c], tnew);
;         float alpha = __builtin_amdgcn_exp2f(mrun[c] - mnew);
;         mrun[c] = mnew; lsum[c] *= alpha;
;         _Pragma("unroll") for (int v = 0; v < NVT; ++v) _Pragma("unroll") for (int j = 0; j < 4; ++j) O[c][v][j] *= alpha;
;       }
.Lda_resc1:
	ds_swizzle_b32 v175, v174 offset:swizzle(SWAP,16)
	s_waitcnt lgkmcnt(0)
	v_max_f32_e32 v174, v174, v175
	s_nop 0
	ds_bpermute_b32 v175, v189, v174
	s_waitcnt lgkmcnt(0)
	v_max3_f32 v175, v171, v174, v175
	v_sub_f32_e32 v174, v171, v175
	v_exp_f32_e32 v174, v174
	v_mov_b32_e32 v171, v175
	v_mul_f32_e32 v191, v191, v174
	v_pk_mul_f32 v[110:111], v[110:111], v[174:175] op_sel_hi:[1,0]
	v_pk_mul_f32 v[112:113], v[112:113], v[174:175] op_sel_hi:[1,0]
	v_pk_mul_f32 v[102:103], v[102:103], v[174:175] op_sel_hi:[1,0]
	v_pk_mul_f32 v[104:105], v[104:105], v[174:175] op_sel_hi:[1,0]
	v_pk_mul_f32 v[94:95], v[94:95], v[174:175] op_sel_hi:[1,0]
	v_pk_mul_f32 v[96:97], v[96:97], v[174:175] op_sel_hi:[1,0]
	v_pk_mul_f32 v[74:75], v[74:75], v[174:175] op_sel_hi:[1,0]
	v_pk_mul_f32 v[76:77], v[76:77], v[174:175] op_sel_hi:[1,0]
	v_pk_mul_f32 v[70:71], v[70:71], v[174:175] op_sel_hi:[1,0]
	v_pk_mul_f32 v[72:73], v[72:73], v[174:175] op_sel_hi:[1,0]
	v_pk_mul_f32 v[66:67], v[66:67], v[174:175] op_sel_hi:[1,0]
	v_pk_mul_f32 v[68:69], v[68:69], v[174:175] op_sel_hi:[1,0]
	v_pk_mul_f32 v[58:59], v[58:59], v[174:175] op_sel_hi:[1,0]
	v_pk_mul_f32 v[60:61], v[60:61], v[174:175] op_sel_hi:[1,0]
	v_pk_mul_f32 v[86:87], v[86:87], v[174:175] op_sel_hi:[1,0]
	v_pk_mul_f32 v[88:89], v[88:89], v[174:175] op_sel_hi:[1,0]
	s_branch .Lda_resc1_ret
.LBB0_1808:
	s_add_i32 s28, s28, s70
	s_cmpk_gt_i32 s28, 0x7ff
	s_cselect_b64 s[12:13], -1, 0
	s_and_b32 s0, s30, 1
	s_mul_i32 s1, s0, 0x4400
	s_add_i32 s34, s1, 0
	v_add3_u32 v0, s34, v210, v204
	s_mul_hi_u32 s0, s30, 0xaaaaaaab
	s_lshr_b32 s0, s0, 1
	s_mul_i32 s0, s0, 3
	s_sub_i32 s0, s30, s0
	s_mul_i32 s0, s0, 0x5000
	s_waitcnt vmcnt(3)
	ds_write_b128 v0, v[34:37]
	v_add3_u32 v0, s34, v209, v205
	s_mov_b32 s31, s0
	s_waitcnt vmcnt(2)
	ds_write_b128 v0, v[38:41]
	v_lshl_add_u32 v0, v206, 1, s31
	v_add3_u32 v0, v0, v211, v212
	v_add_u32_e32 v1, v0, v208
	v_add_u32_e32 v0, v0, v207
	v_add_u32_e32 v1, 0x8800, v1
	v_add_u32_e32 v0, 0x8800, v0
	s_and_b64 vcc, exec, s[12:13]
	s_waitcnt vmcnt(0)
	ds_write2_b64 v1, v[42:43], v[44:45] offset1:2
	ds_write2_b64 v0, v[46:47], v[48:49] offset1:2
	s_waitcnt lgkmcnt(0)
	s_barrier
	s_cbranch_vccnz .LBB0_1810
	s_ashr_i32 s0, s28, 9
	s_ashr_i32 s1, s0, 31
	s_lshl_b64 s[6:7], s[0:1], 24
	s_add_u32 s1, s22, s6
	s_addc_u32 s6, s23, s7
	s_lshl_b32 s7, s28, 7
	s_and_b32 s7, s7, 0x380
	s_lshl_b32 s8, s7, 1
	s_add_u32 s80, s1, s8
	s_addc_u32 s6, s6, 0
	s_lshl_b32 s0, s0, 10
	s_or_b32 s0, s0, s7
	s_ashr_i32 s1, s0, 31
	s_lshl_b64 s[0:1], s[0:1], 14
	v_readlane_b32 s36, v254, 26
	v_readlane_b32 s39, v254, 29
	s_add_u32 s36, s24, s0
	v_readlane_b32 s37, v254, 27
	v_readlane_b32 s38, v254, 28
	s_addc_u32 s0, s25, s1
	s_and_b32 s81, s6, 0xffff
	s_mov_b32 s83, s39
	s_and_b32 s37, s0, 0xffff
	s_mov_b32 s38, s82
	buffer_load_dwordx4 v[34:37], v198, s[80:83], 0 offen
	buffer_load_dwordx4 v[38:41], v199, s[80:83], 0 offen
	buffer_load_dwordx4 v[42:45], v201, s[36:39], 0 offen
	buffer_load_dwordx4 v[46:49], v200, s[36:39], 0 offen
	s_mov_b32 s7, s39
	v_writelane_b32 v254, s4, 26
	s_nop 1
	v_writelane_b32 v254, s5, 27
	v_writelane_b32 v254, s6, 28
	v_writelane_b32 v254, s7, 29
